# same interleaved exp/PV fast path also in NSA sliding-window and selected-block loops
# speedup vs baseline: 1.0334x; 1.0101x over previous
; #define LAS __attribute__((address_space(3)))
; __device__ __forceinline__ float fexp2(float x) { return __builtin_amdgcn_exp2f(x); }
; __device__ __forceinline__ float fmax3(float a, float b, float c) { float d; asm("v_max3_f32 %0, %1, %2, %3" : "=v"(d) : "v"(a), "v"(b), "v"(c)); return d; }
; template <int MODE, int DK, bool PASS2> ...
;     ...
;                     float mx = fmaxf(s0[0], s1[0]);
; #pragma unroll
;                     for (int r = 1; r < 16; ++r) mx = fmax3(mx, s0[r], s1[r]);
;                     if (MODE == M_SLC) mx = selbit ? mx : NEG;
;                     mx = xhalf_max(mx);
;                     const float mxs = mx * sl2;
;                     const float mn = (mxs > m_run + 8.0f) ? mxs : m_run;
;                     const float alpha = fexp2(m_run - mn);
;                     m_run = mn;
;                     float nm = -mn;
;                     if (MODE == M_SLC) nm = selbit ? nm : -__builtin_inff();
;                     float ps0 = 0.f, ps1 = 0.f;
; #pragma unroll
;                     for (int r = 0; r < 16; ++r) {
;                         s0[r] = fexp2(__builtin_fmaf(s0[r], sl2, nm)); s1[r] = fexp2(__builtin_fmaf(s1[r], sl2, nm));
;                         ps0 += s0[r]; ps1 += s1[r];
;                     }
;                     l_run = l_run * alpha + (ps0 + ps1);
;                     if (__builtin_amdgcn_ballot_w64(alpha != 1.0f) != 0ull) {
; #pragma unroll
;                         for (int db = 0; db < 4; ++db)
; #pragma unroll
;                             for (int r = 0; r < 16; ++r) O[db][r] *= alpha;
;                     }
;     ...
;                     const LAS unsigned char* vb = lds + F_VB0 + buf * F_VBS + ql * 144 + g * 16;
;                     __builtin_amdgcn_s_setprio(1);
; #pragma unroll
;                     for (int db = 0; db < 4; ++db)
; #pragma unroll
;                         for (int k2 = 0; k2 < 4; ++k2) {
;                             const bf16x8 vf = *(const LAS bf16x8*)(vb + db * 32 * 144 + k2 * 32);
.Lfast_diff:
	s_mul_i32 s98, s58, 0x4800
	v_add_u32_e32 v210, s98, v201
	ds_read_b128 v[212:215], v210 offset:34816
	ds_read_b128 v[216:219], v210 offset:39424
	ds_read_b128 v[220:223], v210 offset:44032
	ds_read_b128 v[224:227], v210 offset:48640
	ds_read_b128 v[228:231], v210 offset:34848
	ds_read_b128 v[232:235], v210 offset:39456
	v_max_f32_e32 v160, v82, v83
	v_max_f32_e32 v161, v98, v99
	v_max3_f32 v160, v160, v84, v85
	v_max3_f32 v161, v161, v100, v101
	v_max3_f32 v160, v160, v86, v87
	v_max3_f32 v161, v161, v102, v103
	v_max3_f32 v160, v160, v88, v89
	v_max3_f32 v161, v161, v104, v105
	v_max3_f32 v160, v160, v90, v91
	v_max3_f32 v161, v161, v106, v107
	v_max3_f32 v160, v160, v92, v93
	v_max3_f32 v161, v161, v108, v109
	v_max3_f32 v160, v160, v94, v95
	v_max3_f32 v161, v161, v110, v111
	v_max3_f32 v160, v160, v96, v97
	v_max3_f32 v161, v161, v112, v113
	v_max_f32_e32 v160, v160, v161
	v_mov_b32_e32 v161, v160
	s_nop 1
	v_permlane32_swap_b32_e32 v160, v161
	v_max_f32_e32 v160, v160, v161
	v_mul_f32_e32 v160, 0x3e38aa3b, v160
	v_cmp_gt_f32_e32 vcc, v160, v208
	s_nop 1
	v_cndmask_b32_e32 v207, v178, v160, vcc
	v_sub_f32_e32 v161, v178, v207
	v_exp_f32_e32 v178, v161
	s_nop 0
	v_cmp_neq_f32_e32 vcc, 1.0, v178
	s_cbranch_vccz .Lfast_diff_norescale
	v_pk_mul_f32 v[80:81], v[80:81], v[178:179] op_sel_hi:[1,0]
	v_pk_mul_f32 v[78:79], v[78:79], v[178:179] op_sel_hi:[1,0]
	v_pk_mul_f32 v[76:77], v[76:77], v[178:179] op_sel_hi:[1,0]
	v_pk_mul_f32 v[74:75], v[74:75], v[178:179] op_sel_hi:[1,0]
	v_pk_mul_f32 v[72:73], v[72:73], v[178:179] op_sel_hi:[1,0]
	v_pk_mul_f32 v[70:71], v[70:71], v[178:179] op_sel_hi:[1,0]
	v_pk_mul_f32 v[68:69], v[68:69], v[178:179] op_sel_hi:[1,0]
	v_pk_mul_f32 v[66:67], v[66:67], v[178:179] op_sel_hi:[1,0]
	v_pk_mul_f32 v[64:65], v[64:65], v[178:179] op_sel_hi:[1,0]
	v_pk_mul_f32 v[62:63], v[62:63], v[178:179] op_sel_hi:[1,0]
	v_pk_mul_f32 v[60:61], v[60:61], v[178:179] op_sel_hi:[1,0]
	v_pk_mul_f32 v[58:59], v[58:59], v[178:179] op_sel_hi:[1,0]
	v_pk_mul_f32 v[56:57], v[56:57], v[178:179] op_sel_hi:[1,0]
	v_pk_mul_f32 v[54:55], v[54:55], v[178:179] op_sel_hi:[1,0]
	v_pk_mul_f32 v[52:53], v[52:53], v[178:179] op_sel_hi:[1,0]
	v_pk_mul_f32 v[50:51], v[50:51], v[178:179] op_sel_hi:[1,0]
	v_pk_mul_f32 v[48:49], v[48:49], v[178:179] op_sel_hi:[1,0]
	v_pk_mul_f32 v[46:47], v[46:47], v[178:179] op_sel_hi:[1,0]
	v_pk_mul_f32 v[44:45], v[44:45], v[178:179] op_sel_hi:[1,0]
	v_pk_mul_f32 v[42:43], v[42:43], v[178:179] op_sel_hi:[1,0]
	v_pk_mul_f32 v[40:41], v[40:41], v[178:179] op_sel_hi:[1,0]
	v_pk_mul_f32 v[38:39], v[38:39], v[178:179] op_sel_hi:[1,0]
	v_pk_mul_f32 v[36:37], v[36:37], v[178:179] op_sel_hi:[1,0]
	v_pk_mul_f32 v[34:35], v[34:35], v[178:179] op_sel_hi:[1,0]
	v_pk_mul_f32 v[32:33], v[32:33], v[178:179] op_sel_hi:[1,0]
	v_pk_mul_f32 v[30:31], v[30:31], v[178:179] op_sel_hi:[1,0]
	v_pk_mul_f32 v[28:29], v[28:29], v[178:179] op_sel_hi:[1,0]
	v_pk_mul_f32 v[26:27], v[26:27], v[178:179] op_sel_hi:[1,0]
	v_pk_mul_f32 v[24:25], v[24:25], v[178:179] op_sel_hi:[1,0]
	v_pk_mul_f32 v[22:23], v[22:23], v[178:179] op_sel_hi:[1,0]
	v_pk_mul_f32 v[20:21], v[20:21], v[178:179] op_sel_hi:[1,0]
	v_pk_mul_f32 v[18:19], v[18:19], v[178:179] op_sel_hi:[1,0]

; template <int MODE, int DK, bool PASS2> ...
;     ...
;             const int kv0 = j * 64;
;             const int pos_min = (MODE == M_CMP) ? 16 * kv0 + 31 : kv0;
;             const int pos_max = (MODE == M_CMP) ? 16 * (kv0 + 63) + 31 : kv0 + 63;
;             bool active = pos_min <= t_wmax;
;             if (MODE == M_WIN) active = active && (t_wmin - pos_max < 512);
;             bool selbit = true;
;             if (MODE == M_SLC) {
;                 selbit = ((((const LAS unsigned*)impw)[j >> 5] >> (j & 31)) & 1u) != 0u;
;                 active = active && (__builtin_amdgcn_ballot_w64(selbit) != 0ull);
;             }
;             if (active) {
;                 f32x16 s0, s1;
;                 if (MODE == M_FOX) {
;                     const LAS float* ct = (const LAS float*)(lds + F_CT + buf * 256) + 8 * g;
; #pragma unroll
;                     for (int q4 = 0; q4 < 4; ++q4) {
;                         const f32x4 a = *(const LAS f32x4*)(ct + (q4 >> 1) * 16 + (q4 & 1) * 4), b = *(const LAS f32x4*)(ct + 32 + (q4 >> 1) * 16 + (q4 & 1) * 4);
; #pragma unroll
;                         for (int e = 0; e < 4; ++e) { s0[q4 * 4 + e] = a[e]; s1[q4 * 4 + e] = b[e]; }
;                     }
;                 } else { s0 = (f32x16)(0.f); s1 = (f32x16)(0.f); }
;                 const LAS unsigned char* kb = lds + F_KB0 + buf * F_KBS + g * 16 + prow * KSTR;
;                 __builtin_amdgcn_s_setprio(1);
; #pragma unroll
;                 for (int kk = 0; kk < DK / 16; ++kk) {
;                     const bf16x8 a0 = *(const LAS bf16x8*)(kb + kk * 32);
;                     const bf16x8 a1 = *(const LAS bf16x8*)(kb + 32 * KSTR + kk * 32);
;                     s0 = mfma32(a0, qf[kk], s0); s1 = mfma32(a1, qf[kk], s1);
;                 }
;                 __builtin_amdgcn_s_setprio(0);
;                 const bool need_causal = pos_max > t_wmin;
;                 const bool need_bias = (MODE != M_FOX) && ((t_wmin - pos_max) < 128);
;                 const bool need_win = (MODE == M_WIN) && (t_wmax - pos_min >= 512);
;                 if (!PASS2 && !(need_causal || need_bias || need_win)) {
;                     float mx = fmaxf(s0[0], s1[0]);
; #pragma unroll
;                     for (int r = 1; r < 16; ++r) mx = fmax3(mx, s0[r], s1[r]);
;                     if (MODE == M_SLC) mx = selbit ? mx : NEG;
;                     mx = xhalf_max(mx);
.LBB0_2164:
	v_add_u32_e32 v2, 0xffffffa2, v201
	v_cmp_le_i32_e32 vcc, s88, v192
	v_cmp_gt_i32_e64 s[4:5], s82, v2
	s_and_b64 s[4:5], vcc, s[4:5]
	s_and_saveexec_b64 s[68:69], s[4:5]
	s_cbranch_execz .LBB0_2240
	s_mul_i32 s5, s89, 0x4400
	s_add_i32 s4, s88, 63
	v_add_u32_e32 v16, s5, v200
	s_setprio 1
	ds_read_b128 v[4:7], v16
	ds_read_b128 v[8:11], v16 offset:32
	s_waitcnt lgkmcnt(1)
	v_mfma_f32_32x32x16_bf16 v[98:113], v[4:7], v[114:117], 0
	ds_read_b128 v[4:7], v16 offset:8704
	ds_read_b128 v[12:15], v16 offset:8736
	s_waitcnt lgkmcnt(1)
	v_mfma_f32_32x32x16_bf16 v[82:97], v[4:7], v[114:117], 0
	v_mfma_f32_32x32x16_bf16 v[98:113], v[8:11], v[118:121], v[98:113]
	ds_read_b128 v[4:7], v16 offset:64
	ds_read_b128 v[8:11], v16 offset:96
	s_waitcnt lgkmcnt(2)
	v_mfma_f32_32x32x16_bf16 v[82:97], v[12:15], v[118:121], v[82:97]
	s_waitcnt lgkmcnt(1)
	v_mfma_f32_32x32x16_bf16 v[98:113], v[4:7], v[122:125], v[98:113]
	ds_read_b128 v[4:7], v16 offset:8768
	ds_read_b128 v[12:15], v16 offset:8800
	s_waitcnt lgkmcnt(1)
	v_mfma_f32_32x32x16_bf16 v[82:97], v[4:7], v[122:125], v[82:97]
	v_mfma_f32_32x32x16_bf16 v[98:113], v[8:11], v[126:129], v[98:113]
	ds_read_b128 v[4:7], v16 offset:128
	ds_read_b128 v[8:11], v16 offset:160
	s_waitcnt lgkmcnt(2)
	v_mfma_f32_32x32x16_bf16 v[82:97], v[12:15], v[126:129], v[82:97]
	s_waitcnt lgkmcnt(1)
	v_mfma_f32_32x32x16_bf16 v[98:113], v[4:7], v[130:133], v[98:113]
	ds_read_b128 v[4:7], v16 offset:8832
	ds_read_b128 v[12:15], v16 offset:8864
	s_waitcnt lgkmcnt(1)
	v_mfma_f32_32x32x16_bf16 v[82:97], v[4:7], v[130:133], v[82:97]
	v_mfma_f32_32x32x16_bf16 v[98:113], v[8:11], v[134:137], v[98:113]
	ds_read_b128 v[4:7], v16 offset:192
	ds_read_b128 v[8:11], v16 offset:224
	s_waitcnt lgkmcnt(2)
	v_mfma_f32_32x32x16_bf16 v[82:97], v[12:15], v[134:137], v[82:97]
	s_waitcnt lgkmcnt(1)
	v_mfma_f32_32x32x16_bf16 v[98:113], v[4:7], v[138:141], v[98:113]
	ds_read_b128 v[4:7], v16 offset:8896
	ds_read_b128 v[12:15], v16 offset:8928
	s_waitcnt lgkmcnt(1)
	v_mfma_f32_32x32x16_bf16 v[82:97], v[4:7], v[138:141], v[82:97]
	v_mfma_f32_32x32x16_bf16 v[98:113], v[8:11], v[142:145], v[98:113]
	s_waitcnt lgkmcnt(0)
	v_mfma_f32_32x32x16_bf16 v[82:97], v[12:15], v[142:145], v[82:97]
	s_setprio 0
	v_cmp_gt_i32_e32 vcc, s4, v190
	v_cmp_lt_i32_e64 s[6:7], s45, v201
	v_cmp_gt_i32_e64 s[4:5], s76, v2
	s_or_b64 s[8:9], vcc, s[6:7]
	s_nor_b64 s[8:9], s[8:9], s[4:5]
	v_add_f32_e32 v2, 0x41000000, v207
	s_and_saveexec_b64 s[10:11], s[8:9]
	s_xor_b64 s[8:9], exec, s[10:11]
	s_cbranch_execz .LBB0_2169
	s_cmp_eq_u64 s[8:9], 0
	s_cbranch_scc1 .Lfast_win
	s_nop 1
	v_max_f32_e32 v4, v82, v82
	v_max_f32_e32 v5, v98, v98
	v_max_f32_e32 v4, v5, v4
	v_max3_f32 v4, v4, v99, v83
	s_nop 0
	v_max3_f32 v4, v4, v100, v84
	s_nop 0
	v_max3_f32 v4, v4, v101, v85
	s_nop 0
	v_max3_f32 v4, v4, v102, v86
	s_nop 0
	v_max3_f32 v4, v4, v103, v87
	s_nop 0
	v_max3_f32 v4, v4, v104, v88
	s_nop 0
	v_max3_f32 v4, v4, v105, v89
	s_nop 0
	v_max3_f32 v4, v4, v106, v90
	s_nop 0
	v_max3_f32 v4, v4, v107, v91
	s_nop 0
	v_max3_f32 v4, v4, v108, v92
	s_nop 0
	v_max3_f32 v4, v4, v109, v93
	s_nop 0
	v_max3_f32 v4, v4, v110, v94
	s_nop 0
	v_max3_f32 v4, v4, v111, v95
	s_nop 0
	v_max3_f32 v4, v4, v112, v96
	s_nop 0
	v_max3_f32 v4, v4, v113, v97
	s_nop 0
	v_mov_b32_e32 v5, v4
	s_nop 1
	v_permlane32_swap_b32_e32 v4, v5
	v_max_f32_e32 v5, v5, v5
	v_max_f32_e32 v4, v4, v4
	v_max_f32_e32 v4, v4, v5
	v_mul_f32_e32 v4, 0x3e0293ee, v4
	v_cmp_gt_f32_e32 vcc, v4, v2
	s_nop 1
	v_cndmask_b32_e32 v208, v207, v4, vcc
	v_sub_f32_e32 v2, v207, v208
	v_exp_f32_e32 v2, v2
	s_nop 0
	v_cmp_neq_f32_e32 vcc, 1.0, v2
	s_cbranch_vccz .LBB0_2168
	v_pk_mul_f32 v[80:81], v[80:81], v[2:3] op_sel_hi:[1,0]
	v_pk_mul_f32 v[78:79], v[78:79], v[2:3] op_sel_hi:[1,0]
	v_pk_mul_f32 v[76:77], v[76:77], v[2:3] op_sel_hi:[1,0]
	v_pk_mul_f32 v[74:75], v[74:75], v[2:3] op_sel_hi:[1,0]
	v_pk_mul_f32 v[72:73], v[72:73], v[2:3] op_sel_hi:[1,0]
	v_pk_mul_f32 v[70:71], v[70:71], v[2:3] op_sel_hi:[1,0]
	v_pk_mul_f32 v[68:69], v[68:69], v[2:3] op_sel_hi:[1,0]
	v_pk_mul_f32 v[66:67], v[66:67], v[2:3] op_sel_hi:[1,0]
	v_pk_mul_f32 v[64:65], v[64:65], v[2:3] op_sel_hi:[1,0]
	v_pk_mul_f32 v[62:63], v[62:63], v[2:3] op_sel_hi:[1,0]
	v_pk_mul_f32 v[60:61], v[60:61], v[2:3] op_sel_hi:[1,0]
	v_pk_mul_f32 v[58:59], v[58:59], v[2:3] op_sel_hi:[1,0]
	v_pk_mul_f32 v[56:57], v[56:57], v[2:3] op_sel_hi:[1,0]
	v_pk_mul_f32 v[54:55], v[54:55], v[2:3] op_sel_hi:[1,0]
	v_pk_mul_f32 v[52:53], v[52:53], v[2:3] op_sel_hi:[1,0]
	v_pk_mul_f32 v[50:51], v[50:51], v[2:3] op_sel_hi:[1,0]
	v_pk_mul_f32 v[48:49], v[48:49], v[2:3] op_sel_hi:[1,0]
	v_pk_mul_f32 v[46:47], v[46:47], v[2:3] op_sel_hi:[1,0]
	v_pk_mul_f32 v[44:45], v[44:45], v[2:3] op_sel_hi:[1,0]
	v_pk_mul_f32 v[42:43], v[42:43], v[2:3] op_sel_hi:[1,0]
	v_pk_mul_f32 v[40:41], v[40:41], v[2:3] op_sel_hi:[1,0]
	v_pk_mul_f32 v[38:39], v[38:39], v[2:3] op_sel_hi:[1,0]
	v_pk_mul_f32 v[36:37], v[36:37], v[2:3] op_sel_hi:[1,0]
	v_pk_mul_f32 v[34:35], v[34:35], v[2:3] op_sel_hi:[1,0]
	v_pk_mul_f32 v[32:33], v[32:33], v[2:3] op_sel_hi:[1,0]
	v_pk_mul_f32 v[30:31], v[30:31], v[2:3] op_sel_hi:[1,0]
	v_pk_mul_f32 v[28:29], v[28:29], v[2:3] op_sel_hi:[1,0]
	v_pk_mul_f32 v[26:27], v[26:27], v[2:3] op_sel_hi:[1,0]
	v_pk_mul_f32 v[24:25], v[24:25], v[2:3] op_sel_hi:[1,0]
	v_pk_mul_f32 v[22:23], v[22:23], v[2:3] op_sel_hi:[1,0]
	v_pk_mul_f32 v[20:21], v[20:21], v[2:3] op_sel_hi:[1,0]
	v_pk_mul_f32 v[18:19], v[18:19], v[2:3] op_sel_hi:[1,0]

; template <int MODE, int DK, bool PASS2> ...
;     ...
;         if (has) write_tile(buf ^ 1);
;         if (MODE == M_FOX) { if (__syncthreads_and(dead ? 1 : 0)) break; }
;         else __syncthreads();
;         if (!has) break;
;         j = jn; buf ^= 1;
.Lpostpv_win:
	v_mov_b32_e32 v206, v209
	v_mov_b32_e32 v207, v208

; #define LAS __attribute__((address_space(3)))
; __device__ __forceinline__ float fexp2(float x) { return __builtin_amdgcn_exp2f(x); }
; __device__ __forceinline__ float fmax3(float a, float b, float c) { float d; asm("v_max3_f32 %0, %1, %2, %3" : "=v"(d) : "v"(a), "v"(b), "v"(c)); return d; }
; template <int MODE, int DK, bool PASS2> ...
;     ...
;                     float mx = fmaxf(s0[0], s1[0]);
; #pragma unroll
;                     for (int r = 1; r < 16; ++r) mx = fmax3(mx, s0[r], s1[r]);
;                     if (MODE == M_SLC) mx = selbit ? mx : NEG;
;                     mx = xhalf_max(mx);
;                     const float mxs = mx * sl2;
;                     const float mn = (mxs > m_run + 8.0f) ? mxs : m_run;
;                     const float alpha = fexp2(m_run - mn);
;                     m_run = mn;
;                     float nm = -mn;
;                     if (MODE == M_SLC) nm = selbit ? nm : -__builtin_inff();
;                     float ps0 = 0.f, ps1 = 0.f;
; #pragma unroll
;                     for (int r = 0; r < 16; ++r) {
;                         s0[r] = fexp2(__builtin_fmaf(s0[r], sl2, nm)); s1[r] = fexp2(__builtin_fmaf(s1[r], sl2, nm));
;                         ps0 += s0[r]; ps1 += s1[r];
;                     }
;                     l_run = l_run * alpha + (ps0 + ps1);
;                     if (__builtin_amdgcn_ballot_w64(alpha != 1.0f) != 0ull) {
; #pragma unroll
;                         for (int db = 0; db < 4; ++db)
; #pragma unroll
;                             for (int r = 0; r < 16; ++r) O[db][r] *= alpha;
;                     }
;     ...
;                     const LAS unsigned char* vb = lds + F_VB0 + buf * F_VBS + ql * 144 + g * 16;
;                     __builtin_amdgcn_s_setprio(1);
; #pragma unroll
;                     for (int db = 0; db < 4; ++db)
; #pragma unroll
;                         for (int k2 = 0; k2 < 4; ++k2) {
;                             const bf16x8 vf = *(const LAS bf16x8*)(vb + db * 32 * 144 + k2 * 32);
.Lfast_win:
	s_mul_i32 s98, s89, 0x4800
	v_add_u32_e32 v210, s98, v199
	ds_read_b128 v[212:215], v210 offset:34816
	ds_read_b128 v[216:219], v210 offset:39424
	ds_read_b128 v[220:223], v210 offset:44032
	ds_read_b128 v[224:227], v210 offset:48640
	ds_read_b128 v[228:231], v210 offset:34848
	ds_read_b128 v[232:235], v210 offset:39456
	v_max_f32_e32 v166, v98, v99
	v_max_f32_e32 v167, v82, v83
	v_max3_f32 v166, v166, v100, v101
	v_max3_f32 v167, v167, v84, v85
	v_max3_f32 v166, v166, v102, v103
	v_max3_f32 v167, v167, v86, v87
	v_max3_f32 v166, v166, v104, v105
	v_max3_f32 v167, v167, v88, v89
	v_max3_f32 v166, v166, v106, v107
	v_max3_f32 v167, v167, v90, v91
	v_max3_f32 v166, v166, v108, v109
	v_max3_f32 v167, v167, v92, v93
	v_max3_f32 v166, v166, v110, v111
	v_max3_f32 v167, v167, v94, v95
	v_max3_f32 v166, v166, v112, v113
	v_max3_f32 v167, v167, v96, v97
	v_max_f32_e32 v166, v166, v167
	v_mov_b32_e32 v167, v166
	s_nop 1
	v_permlane32_swap_b32_e32 v166, v167
	v_max_f32_e32 v166, v166, v167
	v_mul_f32_e32 v166, 0x3e0293ee, v166
	v_cmp_gt_f32_e32 vcc, v166, v2
	s_nop 1
	v_cndmask_b32_e32 v208, v207, v166, vcc
	v_sub_f32_e32 v167, v207, v208
	v_exp_f32_e32 v2, v167
	s_nop 0
	v_cmp_neq_f32_e32 vcc, 1.0, v2
	s_cbranch_vccz .Lfast_win_norescale
	v_pk_mul_f32 v[80:81], v[80:81], v[2:3] op_sel_hi:[1,0]
	v_pk_mul_f32 v[78:79], v[78:79], v[2:3] op_sel_hi:[1,0]
	v_pk_mul_f32 v[76:77], v[76:77], v[2:3] op_sel_hi:[1,0]
	v_pk_mul_f32 v[74:75], v[74:75], v[2:3] op_sel_hi:[1,0]
	v_pk_mul_f32 v[72:73], v[72:73], v[2:3] op_sel_hi:[1,0]
	v_pk_mul_f32 v[70:71], v[70:71], v[2:3] op_sel_hi:[1,0]
	v_pk_mul_f32 v[68:69], v[68:69], v[2:3] op_sel_hi:[1,0]
	v_pk_mul_f32 v[66:67], v[66:67], v[2:3] op_sel_hi:[1,0]
	v_pk_mul_f32 v[64:65], v[64:65], v[2:3] op_sel_hi:[1,0]
	v_pk_mul_f32 v[62:63], v[62:63], v[2:3] op_sel_hi:[1,0]
	v_pk_mul_f32 v[60:61], v[60:61], v[2:3] op_sel_hi:[1,0]
	v_pk_mul_f32 v[58:59], v[58:59], v[2:3] op_sel_hi:[1,0]
	v_pk_mul_f32 v[56:57], v[56:57], v[2:3] op_sel_hi:[1,0]
	v_pk_mul_f32 v[54:55], v[54:55], v[2:3] op_sel_hi:[1,0]
	v_pk_mul_f32 v[52:53], v[52:53], v[2:3] op_sel_hi:[1,0]
	v_pk_mul_f32 v[50:51], v[50:51], v[2:3] op_sel_hi:[1,0]
	v_pk_mul_f32 v[48:49], v[48:49], v[2:3] op_sel_hi:[1,0]
	v_pk_mul_f32 v[46:47], v[46:47], v[2:3] op_sel_hi:[1,0]
	v_pk_mul_f32 v[44:45], v[44:45], v[2:3] op_sel_hi:[1,0]
	v_pk_mul_f32 v[42:43], v[42:43], v[2:3] op_sel_hi:[1,0]
	v_pk_mul_f32 v[40:41], v[40:41], v[2:3] op_sel_hi:[1,0]
	v_pk_mul_f32 v[38:39], v[38:39], v[2:3] op_sel_hi:[1,0]
	v_pk_mul_f32 v[36:37], v[36:37], v[2:3] op_sel_hi:[1,0]
	v_pk_mul_f32 v[34:35], v[34:35], v[2:3] op_sel_hi:[1,0]
	v_pk_mul_f32 v[32:33], v[32:33], v[2:3] op_sel_hi:[1,0]
	v_pk_mul_f32 v[30:31], v[30:31], v[2:3] op_sel_hi:[1,0]
	v_pk_mul_f32 v[28:29], v[28:29], v[2:3] op_sel_hi:[1,0]
	v_pk_mul_f32 v[26:27], v[26:27], v[2:3] op_sel_hi:[1,0]
	v_pk_mul_f32 v[24:25], v[24:25], v[2:3] op_sel_hi:[1,0]
	v_pk_mul_f32 v[22:23], v[22:23], v[2:3] op_sel_hi:[1,0]
	v_pk_mul_f32 v[20:21], v[20:21], v[2:3] op_sel_hi:[1,0]
	v_pk_mul_f32 v[18:19], v[18:19], v[2:3] op_sel_hi:[1,0]
; #define LAS __attribute__((address_space(3)))
; __device__ __forceinline__ unsigned pack2(float lo, float hi) { unsigned r; asm volatile("v_cvt_pk_bf16_f32 %0, %1, %2" : "=v"(r) : "v"(lo), "v"(hi)); return r; }
; __device__ __forceinline__ float fexp2(float x) { return __builtin_amdgcn_exp2f(x); }
; __device__ __forceinline__ f32x16 mfma32(bf16x8 a, bf16x8 b, f32x16 c) { return __builtin_amdgcn_mfma_f32_32x32x16_bf16(a, b, c, 0, 0, 0); }
; template <int MODE, int DK, bool PASS2> ...
;     ...
;                     float ps0 = 0.f, ps1 = 0.f;
; #pragma unroll
;                     for (int r = 0; r < 16; ++r) {
;                         s0[r] = fexp2(__builtin_fmaf(s0[r], sl2, nm)); s1[r] = fexp2(__builtin_fmaf(s1[r], sl2, nm));
;                         ps0 += s0[r]; ps1 += s1[r];
;                     }
;                     l_run = l_run * alpha + (ps0 + ps1);
;     ...
;                 if (!PASS2) {
;                     bf16x8 pf[4];
; #pragma unroll
;                     for (int k2 = 0; k2 < 4; ++k2) {
;                         u32x4 pk;
; #pragma unroll
;                         for (int e = 0; e < 4; ++e) pk[e] = (k2 < 2) ? pack2(s0[(k2 & 1) * 8 + 2 * e], s0[(k2 & 1) * 8 + 2 * e + 1]) : pack2(s1[(k2 & 1) * 8 + 2 * e], s1[(k2 & 1) * 8 + 2 * e + 1]);
;                         pf[k2] = __builtin_bit_cast(bf16x8, pk);
;                     }
;                     const LAS unsigned char* vb = lds + F_VB0 + buf * F_VBS + ql * 144 + g * 16;
;                     __builtin_amdgcn_s_setprio(1);
; #pragma unroll
;                     for (int db = 0; db < 4; ++db)
; #pragma unroll
;                         for (int k2 = 0; k2 < 4; ++k2) {
;                             const bf16x8 vf = *(const LAS bf16x8*)(vb + db * 32 * 144 + k2 * 32);
;                             O[db] = mfma32(vf, pf[k2], O[db]);
;                             if (k2 == 3 && (db & 1)) __builtin_amdgcn_sched_barrier(0);
;                         }
;                     __builtin_amdgcn_s_setprio(0);
.Lfast_win_norescale:
	v_fma_f32 v12, v98, s58, -v208
	v_fma_f32 v13, v99, s58, -v208
	v_exp_f32_e32 v4, v12
	v_exp_f32_e32 v5, v13
	v_fma_f32 v14, v100, s58, -v208
	v_fma_f32 v15, v101, s58, -v208
	v_exp_f32_e32 v6, v14
	v_exp_f32_e32 v7, v15
	v_add_f32_e32 v16, v4, v5
	v_fma_f32 v12, v102, s58, -v208
	v_fma_f32 v13, v103, s58, -v208
	v_exp_f32_e32 v8, v12
	v_exp_f32_e32 v9, v13
	v_cvt_pk_bf16_f32 v236, v4, v5
	v_add_f32_e32 v16, v16, v6
	v_fma_f32 v14, v104, s58, -v208
	v_add_f32_e32 v16, v16, v7
	v_fma_f32 v15, v105, s58, -v208
	v_exp_f32_e32 v10, v14
	v_exp_f32_e32 v11, v15
	v_cvt_pk_bf16_f32 v237, v6, v7
	v_add_f32_e32 v16, v16, v8
	v_add_f32_e32 v16, v16, v9
	v_cvt_pk_bf16_f32 v238, v8, v9
	v_add_f32_e32 v16, v16, v10
	v_add_f32_e32 v16, v16, v11
	v_cvt_pk_bf16_f32 v239, v10, v11
	s_setprio 1
	v_fma_f32 v12, v106, s58, -v208
	v_fma_f32 v13, v107, s58, -v208
	s_waitcnt lgkmcnt(5)
	v_mfma_f32_32x32x16_bf16 v[66:81], v[212:215], v[236:239], v[66:81]
	v_exp_f32_e32 v4, v12
	v_exp_f32_e32 v5, v13
	v_fma_f32 v14, v108, s58, -v208
	v_fma_f32 v15, v109, s58, -v208
	v_exp_f32_e32 v6, v14
	v_exp_f32_e32 v7, v15
	v_add_f32_e32 v16, v16, v4
	s_waitcnt lgkmcnt(4)
	v_mfma_f32_32x32x16_bf16 v[50:65], v[216:219], v[236:239], v[50:65]
	ds_read_b128 v[212:215], v210 offset:44064
	v_fma_f32 v12, v110, s58, -v208
	v_add_f32_e32 v16, v16, v5
	v_fma_f32 v13, v111, s58, -v208
	v_exp_f32_e32 v8, v12
	v_exp_f32_e32 v9, v13
	v_cvt_pk_bf16_f32 v240, v4, v5
	v_add_f32_e32 v16, v16, v6
	s_waitcnt lgkmcnt(4)
	v_mfma_f32_32x32x16_bf16 v[34:49], v[220:223], v[236:239], v[34:49]
	ds_read_b128 v[216:219], v210 offset:48672
	v_fma_f32 v14, v112, s58, -v208
	v_add_f32_e32 v16, v16, v7
	v_fma_f32 v15, v113, s58, -v208
	v_exp_f32_e32 v10, v14
	v_exp_f32_e32 v11, v15
	v_cvt_pk_bf16_f32 v241, v6, v7
	v_add_f32_e32 v16, v16, v8
	s_waitcnt lgkmcnt(4)
	v_mfma_f32_32x32x16_bf16 v[18:33], v[224:227], v[236:239], v[18:33]
	ds_read_b128 v[220:223], v210 offset:34880
	v_add_f32_e32 v16, v16, v9
	v_cvt_pk_bf16_f32 v242, v8, v9
	v_add_f32_e32 v16, v16, v10
	v_add_f32_e32 v16, v16, v11
	v_cvt_pk_bf16_f32 v243, v10, v11
	v_fma_f32 v12, v82, s58, -v208
	v_fma_f32 v13, v83, s58, -v208
	s_waitcnt lgkmcnt(4)
	v_mfma_f32_32x32x16_bf16 v[66:81], v[228:231], v[240:243], v[66:81]
	ds_read_b128 v[224:227], v210 offset:39488
	v_exp_f32_e32 v4, v12
	v_exp_f32_e32 v5, v13
	v_fma_f32 v14, v84, s58, -v208
	v_fma_f32 v15, v85, s58, -v208
	v_exp_f32_e32 v6, v14
	v_exp_f32_e32 v7, v15
	v_add_f32_e32 v17, v4, v5
	s_waitcnt lgkmcnt(4)
	v_mfma_f32_32x32x16_bf16 v[50:65], v[232:235], v[240:243], v[50:65]
	ds_read_b128 v[228:231], v210 offset:44096
	v_fma_f32 v12, v86, s58, -v208
	v_fma_f32 v13, v87, s58, -v208
	v_exp_f32_e32 v8, v12
	v_exp_f32_e32 v9, v13
	v_cvt_pk_bf16_f32 v244, v4, v5
	v_add_f32_e32 v17, v17, v6
	v_fma_f32 v14, v88, s58, -v208
	s_waitcnt lgkmcnt(4)
	v_mfma_f32_32x32x16_bf16 v[34:49], v[212:215], v[240:243], v[34:49]
	ds_read_b128 v[232:235], v210 offset:48704
	v_add_f32_e32 v17, v17, v7
	v_fma_f32 v15, v89, s58, -v208
	v_exp_f32_e32 v10, v14
	v_exp_f32_e32 v11, v15
	v_cvt_pk_bf16_f32 v245, v6, v7
	v_add_f32_e32 v17, v17, v8
	v_add_f32_e32 v17, v17, v9
	s_waitcnt lgkmcnt(4)
	v_mfma_f32_32x32x16_bf16 v[18:33], v[216:219], v[240:243], v[18:33]
	ds_read_b128 v[212:215], v210 offset:34912
	v_cvt_pk_bf16_f32 v246, v8, v9
	v_add_f32_e32 v17, v17, v10
	v_add_f32_e32 v17, v17, v11
	v_cvt_pk_bf16_f32 v247, v10, v11
	v_fma_f32 v12, v90, s58, -v208
	v_fma_f32 v13, v91, s58, -v208
	s_waitcnt lgkmcnt(4)
	v_mfma_f32_32x32x16_bf16 v[66:81], v[220:223], v[244:247], v[66:81]
	ds_read_b128 v[216:219], v210 offset:39520
	v_exp_f32_e32 v4, v12
	v_exp_f32_e32 v5, v13
	v_fma_f32 v14, v92, s58, -v208
	v_fma_f32 v15, v93, s58, -v208
	v_exp_f32_e32 v6, v14
	v_exp_f32_e32 v7, v15
	v_add_f32_e32 v17, v17, v4
	s_waitcnt lgkmcnt(4)
	v_mfma_f32_32x32x16_bf16 v[50:65], v[224:227], v[244:247], v[50:65]
	ds_read_b128 v[220:223], v210 offset:44128
	v_fma_f32 v12, v94, s58, -v208
	v_add_f32_e32 v17, v17, v5
	v_fma_f32 v13, v95, s58, -v208
	v_exp_f32_e32 v8, v12
	v_exp_f32_e32 v9, v13
	v_cvt_pk_bf16_f32 v248, v4, v5
	v_add_f32_e32 v17, v17, v6
	s_waitcnt lgkmcnt(4)
	v_mfma_f32_32x32x16_bf16 v[34:49], v[228:231], v[244:247], v[34:49]
	ds_read_b128 v[224:227], v210 offset:48736
	v_fma_f32 v14, v96, s58, -v208
	v_add_f32_e32 v17, v17, v7
	v_fma_f32 v15, v97, s58, -v208
	v_exp_f32_e32 v10, v14
	v_exp_f32_e32 v11, v15
	v_cvt_pk_bf16_f32 v249, v6, v7
	v_add_f32_e32 v17, v17, v8
	s_waitcnt lgkmcnt(4)
	v_mfma_f32_32x32x16_bf16 v[18:33], v[232:235], v[244:247], v[18:33]
	v_add_f32_e32 v17, v17, v9
	v_cvt_pk_bf16_f32 v250, v8, v9
	v_add_f32_e32 v17, v17, v10
	v_add_f32_e32 v17, v17, v11
	v_cvt_pk_bf16_f32 v251, v10, v11
	v_add_f32_e32 v209, v16, v17
	s_waitcnt lgkmcnt(3)
	v_mfma_f32_32x32x16_bf16 v[66:81], v[212:215], v[248:251], v[66:81]
	v_fmac_f32_e32 v209, v206, v2
	s_waitcnt lgkmcnt(2)
	v_mfma_f32_32x32x16_bf16 v[50:65], v[216:219], v[248:251], v[50:65]
	s_waitcnt lgkmcnt(1)
	v_mfma_f32_32x32x16_bf16 v[34:49], v[220:223], v[248:251], v[34:49]
	s_waitcnt lgkmcnt(0)
	v_mfma_f32_32x32x16_bf16 v[18:33], v[224:227], v[248:251], v[18:33]
	s_setprio 0
	s_branch .Lpostpv_win

; template <int MODE, int DK, bool PASS2> ...
;     ...
;             if (MODE == M_SLC) {
;                 selbit = ((((const LAS unsigned*)impw)[j >> 5] >> (j & 31)) & 1u) != 0u;
;                 active = active && (__builtin_amdgcn_ballot_w64(selbit) != 0ull);
;             }
;             if (active) {
;                 f32x16 s0, s1;
;                 if (MODE == M_FOX) {
;                     const LAS float* ct = (const LAS float*)(lds + F_CT + buf * 256) + 8 * g;
; #pragma unroll
;                     for (int q4 = 0; q4 < 4; ++q4) {
;                         const f32x4 a = *(const LAS f32x4*)(ct + (q4 >> 1) * 16 + (q4 & 1) * 4), b = *(const LAS f32x4*)(ct + 32 + (q4 >> 1) * 16 + (q4 & 1) * 4);
; #pragma unroll
;                         for (int e = 0; e < 4; ++e) { s0[q4 * 4 + e] = a[e]; s1[q4 * 4 + e] = b[e]; }
;                     }
;                 } else { s0 = (f32x16)(0.f); s1 = (f32x16)(0.f); }
;                 const LAS unsigned char* kb = lds + F_KB0 + buf * F_KBS + g * 16 + prow * KSTR;
;                 __builtin_amdgcn_s_setprio(1);
; #pragma unroll
;                 for (int kk = 0; kk < DK / 16; ++kk) {
;                     const bf16x8 a0 = *(const LAS bf16x8*)(kb + kk * 32);
;                     const bf16x8 a1 = *(const LAS bf16x8*)(kb + 32 * KSTR + kk * 32);
;                     s0 = mfma32(a0, qf[kk], s0); s1 = mfma32(a1, qf[kk], s1);
;                 }
;                 __builtin_amdgcn_s_setprio(0);
;                 const bool need_causal = pos_max > t_wmin;
;                 const bool need_bias = (MODE != M_FOX) && ((t_wmin - pos_max) < 128);
;                 const bool need_win = (MODE == M_WIN) && (t_wmax - pos_min >= 512);
;                 if (!PASS2 && !(need_causal || need_bias || need_win)) {
;                     float mx = fmaxf(s0[0], s1[0]);
; #pragma unroll
;                     for (int r = 1; r < 16; ++r) mx = fmax3(mx, s0[r], s1[r]);
;                     if (MODE == M_SLC) mx = selbit ? mx : NEG;
;                     mx = xhalf_max(mx);
;                     const float mxs = mx * sl2;
;                     const float mn = (mxs > m_run + 8.0f) ? mxs : m_run;
;                     const float alpha = fexp2(m_run - mn);
;                     m_run = mn;
;                     float nm = -mn;
;                     if (MODE == M_SLC) nm = selbit ? nm : -__builtin_inff();
.LBB0_2597:
	s_lshl_b32 s78, s48, 6
	v_cmp_le_i32_e32 vcc, s78, v206
	s_and_saveexec_b64 s[38:39], vcc
	s_cbranch_execz .LBB0_2610
	s_ashr_i32 s4, s48, 5
	v_lshl_add_u32 v2, s4, 2, v164
	ds_read_b32 v2, v2
	s_and_b32 s4, s48, 31
	s_waitcnt lgkmcnt(0)
	v_lshrrev_b32_e32 v4, s48, v2
	v_bfe_u32 v2, v2, s4, 1
	v_and_b32_e32 v4, 1, v4
	v_cmp_ne_u32_e32 vcc, 0, v2
	v_cmp_eq_u32_e64 s[4:5], 1, v4
	s_cbranch_vccz .LBB0_2610
	s_mul_i32 s6, s74, 0x4400
	s_or_b32 s48, s78, 63
	v_add_u32_e32 v2, s6, v215
	s_setprio 1
	ds_read_b128 v[4:7], v2
	ds_read_b128 v[8:11], v2 offset:32
	s_waitcnt lgkmcnt(1)
	v_mfma_f32_32x32x16_bf16 v[98:113], v[4:7], v[114:117], 0
	ds_read_b128 v[4:7], v2 offset:8704
	ds_read_b128 v[12:15], v2 offset:8736
	s_waitcnt lgkmcnt(1)
	v_mfma_f32_32x32x16_bf16 v[82:97], v[4:7], v[114:117], 0
	v_mfma_f32_32x32x16_bf16 v[98:113], v[8:11], v[118:121], v[98:113]
	ds_read_b128 v[4:7], v2 offset:64
	ds_read_b128 v[8:11], v2 offset:96
	s_waitcnt lgkmcnt(2)
	v_mfma_f32_32x32x16_bf16 v[82:97], v[12:15], v[118:121], v[82:97]
	s_waitcnt lgkmcnt(1)
	v_mfma_f32_32x32x16_bf16 v[98:113], v[4:7], v[122:125], v[98:113]
	ds_read_b128 v[4:7], v2 offset:8768
	ds_read_b128 v[12:15], v2 offset:8800
	s_waitcnt lgkmcnt(1)
	v_mfma_f32_32x32x16_bf16 v[82:97], v[4:7], v[122:125], v[82:97]
	v_mfma_f32_32x32x16_bf16 v[98:113], v[8:11], v[126:129], v[98:113]
	ds_read_b128 v[4:7], v2 offset:128
	ds_read_b128 v[8:11], v2 offset:160
	s_waitcnt lgkmcnt(2)
	v_mfma_f32_32x32x16_bf16 v[82:97], v[12:15], v[126:129], v[82:97]
	s_waitcnt lgkmcnt(1)
	v_mfma_f32_32x32x16_bf16 v[98:113], v[4:7], v[130:133], v[98:113]
	ds_read_b128 v[4:7], v2 offset:8832
	ds_read_b128 v[12:15], v2 offset:8864
	s_waitcnt lgkmcnt(1)
	v_mfma_f32_32x32x16_bf16 v[82:97], v[4:7], v[130:133], v[82:97]
	v_mfma_f32_32x32x16_bf16 v[98:113], v[8:11], v[134:137], v[98:113]
	ds_read_b128 v[4:7], v2 offset:192
	ds_read_b128 v[8:11], v2 offset:224
	s_waitcnt lgkmcnt(2)
	v_mfma_f32_32x32x16_bf16 v[82:97], v[12:15], v[134:137], v[82:97]
	s_waitcnt lgkmcnt(1)
	v_mfma_f32_32x32x16_bf16 v[98:113], v[4:7], v[138:141], v[98:113]
	ds_read_b128 v[4:7], v2 offset:8896
	ds_read_b128 v[12:15], v2 offset:8928
	s_waitcnt lgkmcnt(1)
	v_mfma_f32_32x32x16_bf16 v[82:97], v[4:7], v[138:141], v[82:97]
	v_mfma_f32_32x32x16_bf16 v[98:113], v[8:11], v[142:145], v[98:113]
	s_waitcnt lgkmcnt(0)
	v_mfma_f32_32x32x16_bf16 v[82:97], v[12:15], v[142:145], v[82:97]
	s_setprio 0
	v_min_i32_e32 v2, v199, v207
	v_cmp_gt_i32_e64 s[6:7], s48, v207
	v_cmp_le_i32_e32 vcc, s48, v2
	v_add_f32_e32 v2, 0x41000000, v217
	s_and_saveexec_b64 s[48:49], vcc
	s_xor_b64 s[48:49], exec, s[48:49]
	s_cbranch_execz .LBB0_2603
	s_cmp_eq_u64 s[48:49], 0
	s_cbranch_scc1 .Lfast_slc
	s_nop 3
	v_max_f32_e32 v4, v82, v82
	v_max_f32_e32 v5, v98, v98
	v_max_f32_e32 v4, v5, v4
	v_max3_f32 v4, v4, v99, v83
	s_nop 0
	v_max3_f32 v4, v4, v100, v84
	s_nop 0
	v_max3_f32 v4, v4, v101, v85
	s_nop 0
	v_max3_f32 v4, v4, v102, v86
	s_nop 0
	v_max3_f32 v4, v4, v103, v87
	s_nop 0
	v_max3_f32 v4, v4, v104, v88
	s_nop 0
	v_max3_f32 v4, v4, v105, v89
	s_nop 0
	v_max3_f32 v4, v4, v106, v90
	s_nop 0
	v_max3_f32 v4, v4, v107, v91
	s_nop 0
	v_max3_f32 v4, v4, v108, v92
	s_nop 0
	v_max3_f32 v4, v4, v109, v93
	s_nop 0
	v_max3_f32 v4, v4, v110, v94
	s_nop 0
	v_max3_f32 v4, v4, v111, v95
	s_nop 0
	v_max3_f32 v4, v4, v112, v96
	s_nop 0
	v_max3_f32 v4, v4, v113, v97
	s_nop 0
	v_cndmask_b32_e64 v4, v194, v4, s[4:5]
	v_mov_b32_e32 v5, v4
	s_nop 1
	v_permlane32_swap_b32_e32 v4, v5
	v_max_f32_e32 v5, v5, v5
	v_max_f32_e32 v4, v4, v4
	v_max_f32_e32 v4, v4, v5
	v_mul_f32_e32 v4, 0x3e0293ee, v4
	v_cmp_gt_f32_e32 vcc, v4, v2
	s_nop 1
	v_cndmask_b32_e32 v218, v217, v4, vcc
	v_sub_f32_e32 v2, v217, v218
	v_exp_f32_e32 v2, v2
	s_nop 0
	v_cmp_neq_f32_e32 vcc, 1.0, v2
	s_cbranch_vccz .LBB0_2602
	v_pk_mul_f32 v[80:81], v[80:81], v[2:3] op_sel_hi:[1,0]
	v_pk_mul_f32 v[78:79], v[78:79], v[2:3] op_sel_hi:[1,0]
	v_pk_mul_f32 v[76:77], v[76:77], v[2:3] op_sel_hi:[1,0]
	v_pk_mul_f32 v[74:75], v[74:75], v[2:3] op_sel_hi:[1,0]
	v_pk_mul_f32 v[72:73], v[72:73], v[2:3] op_sel_hi:[1,0]
	v_pk_mul_f32 v[70:71], v[70:71], v[2:3] op_sel_hi:[1,0]
	v_pk_mul_f32 v[68:69], v[68:69], v[2:3] op_sel_hi:[1,0]
	v_pk_mul_f32 v[66:67], v[66:67], v[2:3] op_sel_hi:[1,0]
	v_pk_mul_f32 v[64:65], v[64:65], v[2:3] op_sel_hi:[1,0]
	v_pk_mul_f32 v[62:63], v[62:63], v[2:3] op_sel_hi:[1,0]
	v_pk_mul_f32 v[60:61], v[60:61], v[2:3] op_sel_hi:[1,0]
	v_pk_mul_f32 v[58:59], v[58:59], v[2:3] op_sel_hi:[1,0]
	v_pk_mul_f32 v[56:57], v[56:57], v[2:3] op_sel_hi:[1,0]
	v_pk_mul_f32 v[54:55], v[54:55], v[2:3] op_sel_hi:[1,0]
	v_pk_mul_f32 v[52:53], v[52:53], v[2:3] op_sel_hi:[1,0]
	v_pk_mul_f32 v[50:51], v[50:51], v[2:3] op_sel_hi:[1,0]
	v_pk_mul_f32 v[48:49], v[48:49], v[2:3] op_sel_hi:[1,0]
	v_pk_mul_f32 v[46:47], v[46:47], v[2:3] op_sel_hi:[1,0]
	v_pk_mul_f32 v[44:45], v[44:45], v[2:3] op_sel_hi:[1,0]
	v_pk_mul_f32 v[42:43], v[42:43], v[2:3] op_sel_hi:[1,0]
	v_pk_mul_f32 v[40:41], v[40:41], v[2:3] op_sel_hi:[1,0]
	v_pk_mul_f32 v[38:39], v[38:39], v[2:3] op_sel_hi:[1,0]
	v_pk_mul_f32 v[36:37], v[36:37], v[2:3] op_sel_hi:[1,0]
	v_pk_mul_f32 v[34:35], v[34:35], v[2:3] op_sel_hi:[1,0]
	v_pk_mul_f32 v[32:33], v[32:33], v[2:3] op_sel_hi:[1,0]
	v_pk_mul_f32 v[30:31], v[30:31], v[2:3] op_sel_hi:[1,0]
	v_pk_mul_f32 v[28:29], v[28:29], v[2:3] op_sel_hi:[1,0]
	v_pk_mul_f32 v[26:27], v[26:27], v[2:3] op_sel_hi:[1,0]
	v_pk_mul_f32 v[24:25], v[24:25], v[2:3] op_sel_hi:[1,0]
	v_pk_mul_f32 v[22:23], v[22:23], v[2:3] op_sel_hi:[1,0]
	v_pk_mul_f32 v[20:21], v[20:21], v[2:3] op_sel_hi:[1,0]
	v_pk_mul_f32 v[18:19], v[18:19], v[2:3] op_sel_hi:[1,0]

; template <int MODE, int DK, bool PASS2> ...
;     ...
;         if (has) write_tile(buf ^ 1);
;         if (MODE == M_FOX) { if (__syncthreads_and(dead ? 1 : 0)) break; }
;         else __syncthreads();
;         if (!has) break;
;         j = jn; buf ^= 1;
.Lpostpv_slc:
	v_mov_b32_e32 v216, v219
	v_mov_b32_e32 v217, v218

; #define LAS __attribute__((address_space(3)))
; __device__ __forceinline__ float fexp2(float x) { return __builtin_amdgcn_exp2f(x); }
; __device__ __forceinline__ float fmax3(float a, float b, float c) { float d; asm("v_max3_f32 %0, %1, %2, %3" : "=v"(d) : "v"(a), "v"(b), "v"(c)); return d; }
; template <int MODE, int DK, bool PASS2> ...
;     ...
;                     float mx = fmaxf(s0[0], s1[0]);
; #pragma unroll
;                     for (int r = 1; r < 16; ++r) mx = fmax3(mx, s0[r], s1[r]);
;                     if (MODE == M_SLC) mx = selbit ? mx : NEG;
;                     mx = xhalf_max(mx);
;                     const float mxs = mx * sl2;
;                     const float mn = (mxs > m_run + 8.0f) ? mxs : m_run;
;                     const float alpha = fexp2(m_run - mn);
;                     m_run = mn;
;                     float nm = -mn;
;                     if (MODE == M_SLC) nm = selbit ? nm : -__builtin_inff();
;                     float ps0 = 0.f, ps1 = 0.f;
; #pragma unroll
;                     for (int r = 0; r < 16; ++r) {
;                         s0[r] = fexp2(__builtin_fmaf(s0[r], sl2, nm)); s1[r] = fexp2(__builtin_fmaf(s1[r], sl2, nm));
;                         ps0 += s0[r]; ps1 += s1[r];
;                     }
;                     l_run = l_run * alpha + (ps0 + ps1);
;                     if (__builtin_amdgcn_ballot_w64(alpha != 1.0f) != 0ull) {
; #pragma unroll
;                         for (int db = 0; db < 4; ++db)
; #pragma unroll
;                             for (int r = 0; r < 16; ++r) O[db][r] *= alpha;
;                     }
;     ...
;                     const LAS unsigned char* vb = lds + F_VB0 + buf * F_VBS + ql * 144 + g * 16;
;                     __builtin_amdgcn_s_setprio(1);
; #pragma unroll
;                     for (int db = 0; db < 4; ++db)
; #pragma unroll
;                         for (int k2 = 0; k2 < 4; ++k2) {
;                             const bf16x8 vf = *(const LAS bf16x8*)(vb + db * 32 * 144 + k2 * 32);
.Lfast_slc:
	s_mul_i32 s98, s74, 0x4800
	v_add_u32_e32 v220, s98, v214
	ds_read_b128 v[222:225], v220 offset:34816
	ds_read_b128 v[226:229], v220 offset:39424
	ds_read_b128 v[230:233], v220 offset:44032
	ds_read_b128 v[234:237], v220 offset:48640
	ds_read_b128 v[238:241], v220 offset:34848
	ds_read_b128 v[242:245], v220 offset:39456
	v_max_f32_e32 v174, v98, v99
	v_max_f32_e32 v175, v82, v83
	v_max3_f32 v174, v174, v100, v101
	v_max3_f32 v175, v175, v84, v85
	v_max3_f32 v174, v174, v102, v103
	v_max3_f32 v175, v175, v86, v87
	v_max3_f32 v174, v174, v104, v105
	v_max3_f32 v175, v175, v88, v89
	v_max3_f32 v174, v174, v106, v107
	v_max3_f32 v175, v175, v90, v91
	v_max3_f32 v174, v174, v108, v109
	v_max3_f32 v175, v175, v92, v93
	v_max3_f32 v174, v174, v110, v111
	v_max3_f32 v175, v175, v94, v95
	v_max3_f32 v174, v174, v112, v113
	v_max3_f32 v175, v175, v96, v97
	v_max_f32_e32 v174, v174, v175
	v_cndmask_b32_e64 v174, v194, v174, s[4:5]
	v_mov_b32_e32 v175, v174
	s_nop 1
	v_permlane32_swap_b32_e32 v174, v175
	v_max_f32_e32 v174, v174, v175
	v_mul_f32_e32 v174, 0x3e0293ee, v174
	v_cmp_gt_f32_e32 vcc, v174, v2
	s_nop 1
	v_cndmask_b32_e32 v218, v217, v174, vcc
	v_sub_f32_e32 v175, v217, v218
	v_exp_f32_e32 v2, v175
	s_nop 0
	v_cmp_neq_f32_e32 vcc, 1.0, v2
	s_cbranch_vccz .Lfast_slc_norescale
	v_pk_mul_f32 v[80:81], v[80:81], v[2:3] op_sel_hi:[1,0]
	v_pk_mul_f32 v[78:79], v[78:79], v[2:3] op_sel_hi:[1,0]
	v_pk_mul_f32 v[76:77], v[76:77], v[2:3] op_sel_hi:[1,0]
	v_pk_mul_f32 v[74:75], v[74:75], v[2:3] op_sel_hi:[1,0]
	v_pk_mul_f32 v[72:73], v[72:73], v[2:3] op_sel_hi:[1,0]
	v_pk_mul_f32 v[70:71], v[70:71], v[2:3] op_sel_hi:[1,0]
	v_pk_mul_f32 v[68:69], v[68:69], v[2:3] op_sel_hi:[1,0]
	v_pk_mul_f32 v[66:67], v[66:67], v[2:3] op_sel_hi:[1,0]
	v_pk_mul_f32 v[64:65], v[64:65], v[2:3] op_sel_hi:[1,0]
	v_pk_mul_f32 v[62:63], v[62:63], v[2:3] op_sel_hi:[1,0]
	v_pk_mul_f32 v[60:61], v[60:61], v[2:3] op_sel_hi:[1,0]
	v_pk_mul_f32 v[58:59], v[58:59], v[2:3] op_sel_hi:[1,0]
	v_pk_mul_f32 v[56:57], v[56:57], v[2:3] op_sel_hi:[1,0]
	v_pk_mul_f32 v[54:55], v[54:55], v[2:3] op_sel_hi:[1,0]
	v_pk_mul_f32 v[52:53], v[52:53], v[2:3] op_sel_hi:[1,0]
	v_pk_mul_f32 v[50:51], v[50:51], v[2:3] op_sel_hi:[1,0]
	v_pk_mul_f32 v[48:49], v[48:49], v[2:3] op_sel_hi:[1,0]
	v_pk_mul_f32 v[46:47], v[46:47], v[2:3] op_sel_hi:[1,0]
	v_pk_mul_f32 v[44:45], v[44:45], v[2:3] op_sel_hi:[1,0]
	v_pk_mul_f32 v[42:43], v[42:43], v[2:3] op_sel_hi:[1,0]
	v_pk_mul_f32 v[40:41], v[40:41], v[2:3] op_sel_hi:[1,0]
	v_pk_mul_f32 v[38:39], v[38:39], v[2:3] op_sel_hi:[1,0]
	v_pk_mul_f32 v[36:37], v[36:37], v[2:3] op_sel_hi:[1,0]
	v_pk_mul_f32 v[34:35], v[34:35], v[2:3] op_sel_hi:[1,0]
	v_pk_mul_f32 v[32:33], v[32:33], v[2:3] op_sel_hi:[1,0]
	v_pk_mul_f32 v[30:31], v[30:31], v[2:3] op_sel_hi:[1,0]
	v_pk_mul_f32 v[28:29], v[28:29], v[2:3] op_sel_hi:[1,0]
	v_pk_mul_f32 v[26:27], v[26:27], v[2:3] op_sel_hi:[1,0]
	v_pk_mul_f32 v[24:25], v[24:25], v[2:3] op_sel_hi:[1,0]
	v_pk_mul_f32 v[22:23], v[22:23], v[2:3] op_sel_hi:[1,0]
	v_pk_mul_f32 v[20:21], v[20:21], v[2:3] op_sel_hi:[1,0]
	v_pk_mul_f32 v[18:19], v[18:19], v[2:3] op_sel_hi:[1,0]
; #define LAS __attribute__((address_space(3)))
; __device__ __forceinline__ unsigned pack2(float lo, float hi) { unsigned r; asm volatile("v_cvt_pk_bf16_f32 %0, %1, %2" : "=v"(r) : "v"(lo), "v"(hi)); return r; }
; __device__ __forceinline__ float fexp2(float x) { return __builtin_amdgcn_exp2f(x); }
; __device__ __forceinline__ f32x16 mfma32(bf16x8 a, bf16x8 b, f32x16 c) { return __builtin_amdgcn_mfma_f32_32x32x16_bf16(a, b, c, 0, 0, 0); }
; template <int MODE, int DK, bool PASS2> ...
;     ...
;                     if (MODE == M_SLC) nm = selbit ? nm : -__builtin_inff();
;                     float ps0 = 0.f, ps1 = 0.f;
; #pragma unroll
;                     for (int r = 0; r < 16; ++r) {
;                         s0[r] = fexp2(__builtin_fmaf(s0[r], sl2, nm)); s1[r] = fexp2(__builtin_fmaf(s1[r], sl2, nm));
;                         ps0 += s0[r]; ps1 += s1[r];
;                     }
;                     l_run = l_run * alpha + (ps0 + ps1);
;     ...
;                 if (!PASS2) {
;                     bf16x8 pf[4];
; #pragma unroll
;                     for (int k2 = 0; k2 < 4; ++k2) {
;                         u32x4 pk;
; #pragma unroll
;                         for (int e = 0; e < 4; ++e) pk[e] = (k2 < 2) ? pack2(s0[(k2 & 1) * 8 + 2 * e], s0[(k2 & 1) * 8 + 2 * e + 1]) : pack2(s1[(k2 & 1) * 8 + 2 * e], s1[(k2 & 1) * 8 + 2 * e + 1]);
;                         pf[k2] = __builtin_bit_cast(bf16x8, pk);
;                     }
;                     const LAS unsigned char* vb = lds + F_VB0 + buf * F_VBS + ql * 144 + g * 16;
;                     __builtin_amdgcn_s_setprio(1);
; #pragma unroll
;                     for (int db = 0; db < 4; ++db)
; #pragma unroll
;                         for (int k2 = 0; k2 < 4; ++k2) {
;                             const bf16x8 vf = *(const LAS bf16x8*)(vb + db * 32 * 144 + k2 * 32);
;                             O[db] = mfma32(vf, pf[k2], O[db]);
;                             if (k2 == 3 && (db & 1)) __builtin_amdgcn_sched_barrier(0);
;                         }
;                     __builtin_amdgcn_s_setprio(0);
.Lfast_slc_norescale:
	v_cndmask_b32_e64 v191, v195, -v218, s[4:5]
	v_fmamk_f32 v12, v98, 0x3e0293ee, v191
	v_fmamk_f32 v13, v99, 0x3e0293ee, v191
	v_exp_f32_e32 v4, v12
	v_exp_f32_e32 v5, v13
	v_fmamk_f32 v14, v100, 0x3e0293ee, v191
	v_fmamk_f32 v15, v101, 0x3e0293ee, v191
	v_exp_f32_e32 v6, v14
	v_exp_f32_e32 v7, v15
	v_add_f32_e32 v16, v4, v5
	v_fmamk_f32 v12, v102, 0x3e0293ee, v191
	v_fmamk_f32 v13, v103, 0x3e0293ee, v191
	v_exp_f32_e32 v8, v12
	v_exp_f32_e32 v9, v13
	v_cvt_pk_bf16_f32 v98, v4, v5
	v_add_f32_e32 v16, v16, v6
	v_fmamk_f32 v14, v104, 0x3e0293ee, v191
	v_add_f32_e32 v16, v16, v7
	v_fmamk_f32 v15, v105, 0x3e0293ee, v191
	v_exp_f32_e32 v10, v14
	v_exp_f32_e32 v11, v15
	v_cvt_pk_bf16_f32 v99, v6, v7
	v_add_f32_e32 v16, v16, v8
	v_add_f32_e32 v16, v16, v9
	v_cvt_pk_bf16_f32 v100, v8, v9
	v_add_f32_e32 v16, v16, v10
	v_add_f32_e32 v16, v16, v11
	v_cvt_pk_bf16_f32 v101, v10, v11
	s_setprio 1
	v_fmamk_f32 v12, v106, 0x3e0293ee, v191
	v_fmamk_f32 v13, v107, 0x3e0293ee, v191
	s_waitcnt lgkmcnt(5)
	v_mfma_f32_32x32x16_bf16 v[66:81], v[222:225], v[98:101], v[66:81]
	v_exp_f32_e32 v4, v12
	v_exp_f32_e32 v5, v13
	v_fmamk_f32 v14, v108, 0x3e0293ee, v191
	v_fmamk_f32 v15, v109, 0x3e0293ee, v191
	v_exp_f32_e32 v6, v14
	v_exp_f32_e32 v7, v15
	v_add_f32_e32 v16, v16, v4
	s_waitcnt lgkmcnt(4)
	v_mfma_f32_32x32x16_bf16 v[50:65], v[226:229], v[98:101], v[50:65]
	ds_read_b128 v[222:225], v220 offset:44064
	v_fmamk_f32 v12, v110, 0x3e0293ee, v191
	v_add_f32_e32 v16, v16, v5
	v_fmamk_f32 v13, v111, 0x3e0293ee, v191
	v_exp_f32_e32 v8, v12
	v_exp_f32_e32 v9, v13
	v_cvt_pk_bf16_f32 v106, v4, v5
	v_add_f32_e32 v16, v16, v6
	s_waitcnt lgkmcnt(4)
	v_mfma_f32_32x32x16_bf16 v[34:49], v[230:233], v[98:101], v[34:49]
	ds_read_b128 v[226:229], v220 offset:48672
	v_fmamk_f32 v14, v112, 0x3e0293ee, v191
	v_add_f32_e32 v16, v16, v7
	v_fmamk_f32 v15, v113, 0x3e0293ee, v191
	v_exp_f32_e32 v10, v14
	v_exp_f32_e32 v11, v15
	v_cvt_pk_bf16_f32 v107, v6, v7
	v_add_f32_e32 v16, v16, v8
	s_waitcnt lgkmcnt(4)
	v_mfma_f32_32x32x16_bf16 v[18:33], v[234:237], v[98:101], v[18:33]
	ds_read_b128 v[230:233], v220 offset:34880
	v_add_f32_e32 v16, v16, v9
	v_cvt_pk_bf16_f32 v108, v8, v9
	v_add_f32_e32 v16, v16, v10
	v_add_f32_e32 v16, v16, v11
	v_cvt_pk_bf16_f32 v109, v10, v11
	v_fmamk_f32 v12, v82, 0x3e0293ee, v191
	v_fmamk_f32 v13, v83, 0x3e0293ee, v191
	s_waitcnt lgkmcnt(4)
	v_mfma_f32_32x32x16_bf16 v[66:81], v[238:241], v[106:109], v[66:81]
	ds_read_b128 v[234:237], v220 offset:39488
	v_exp_f32_e32 v4, v12
	v_exp_f32_e32 v5, v13
	v_fmamk_f32 v14, v84, 0x3e0293ee, v191
	v_fmamk_f32 v15, v85, 0x3e0293ee, v191
	v_exp_f32_e32 v6, v14
	v_exp_f32_e32 v7, v15
	v_add_f32_e32 v17, v4, v5
	s_waitcnt lgkmcnt(4)
	v_mfma_f32_32x32x16_bf16 v[50:65], v[242:245], v[106:109], v[50:65]
	ds_read_b128 v[238:241], v220 offset:44096
	v_fmamk_f32 v12, v86, 0x3e0293ee, v191
	v_fmamk_f32 v13, v87, 0x3e0293ee, v191
	v_exp_f32_e32 v8, v12
	v_exp_f32_e32 v9, v13
	v_cvt_pk_bf16_f32 v82, v4, v5
	v_add_f32_e32 v17, v17, v6
	v_fmamk_f32 v14, v88, 0x3e0293ee, v191
	s_waitcnt lgkmcnt(4)
	v_mfma_f32_32x32x16_bf16 v[34:49], v[222:225], v[106:109], v[34:49]
	ds_read_b128 v[242:245], v220 offset:48704
	v_add_f32_e32 v17, v17, v7
	v_fmamk_f32 v15, v89, 0x3e0293ee, v191
	v_exp_f32_e32 v10, v14
	v_exp_f32_e32 v11, v15
	v_cvt_pk_bf16_f32 v83, v6, v7
	v_add_f32_e32 v17, v17, v8
	v_add_f32_e32 v17, v17, v9
	s_waitcnt lgkmcnt(4)
	v_mfma_f32_32x32x16_bf16 v[18:33], v[226:229], v[106:109], v[18:33]
	ds_read_b128 v[222:225], v220 offset:34912
	v_cvt_pk_bf16_f32 v84, v8, v9
	v_add_f32_e32 v17, v17, v10
	v_add_f32_e32 v17, v17, v11
	v_cvt_pk_bf16_f32 v85, v10, v11
	v_fmamk_f32 v12, v90, 0x3e0293ee, v191
	v_fmamk_f32 v13, v91, 0x3e0293ee, v191
	s_waitcnt lgkmcnt(4)
	v_mfma_f32_32x32x16_bf16 v[66:81], v[230:233], v[82:85], v[66:81]
	ds_read_b128 v[226:229], v220 offset:39520
	v_exp_f32_e32 v4, v12
	v_exp_f32_e32 v5, v13
	v_fmamk_f32 v14, v92, 0x3e0293ee, v191
	v_fmamk_f32 v15, v93, 0x3e0293ee, v191
	v_exp_f32_e32 v6, v14
	v_exp_f32_e32 v7, v15
	v_add_f32_e32 v17, v17, v4
	s_waitcnt lgkmcnt(4)
	v_mfma_f32_32x32x16_bf16 v[50:65], v[234:237], v[82:85], v[50:65]
	ds_read_b128 v[230:233], v220 offset:44128
	v_fmamk_f32 v12, v94, 0x3e0293ee, v191
	v_add_f32_e32 v17, v17, v5
	v_fmamk_f32 v13, v95, 0x3e0293ee, v191
	v_exp_f32_e32 v8, v12
	v_exp_f32_e32 v9, v13
	v_cvt_pk_bf16_f32 v90, v4, v5
	v_add_f32_e32 v17, v17, v6
	s_waitcnt lgkmcnt(4)
	v_mfma_f32_32x32x16_bf16 v[34:49], v[238:241], v[82:85], v[34:49]
	ds_read_b128 v[234:237], v220 offset:48736
	v_fmamk_f32 v14, v96, 0x3e0293ee, v191
	v_add_f32_e32 v17, v17, v7
	v_fmamk_f32 v15, v97, 0x3e0293ee, v191
	v_exp_f32_e32 v10, v14
	v_exp_f32_e32 v11, v15
	v_cvt_pk_bf16_f32 v91, v6, v7
	v_add_f32_e32 v17, v17, v8
	s_waitcnt lgkmcnt(4)
	v_mfma_f32_32x32x16_bf16 v[18:33], v[242:245], v[82:85], v[18:33]
	v_add_f32_e32 v17, v17, v9
	v_cvt_pk_bf16_f32 v92, v8, v9
	v_add_f32_e32 v17, v17, v10
	v_add_f32_e32 v17, v17, v11
	v_cvt_pk_bf16_f32 v93, v10, v11
	v_add_f32_e32 v219, v16, v17
	s_waitcnt lgkmcnt(3)
	v_mfma_f32_32x32x16_bf16 v[66:81], v[222:225], v[90:93], v[66:81]
	v_fmac_f32_e32 v219, v216, v2
	s_waitcnt lgkmcnt(2)
	v_mfma_f32_32x32x16_bf16 v[50:65], v[226:229], v[90:93], v[50:65]
	s_waitcnt lgkmcnt(1)
	v_mfma_f32_32x32x16_bf16 v[34:49], v[230:233], v[90:93], v[34:49]
	s_waitcnt lgkmcnt(0)
	v_mfma_f32_32x32x16_bf16 v[18:33], v[234:237], v[90:93], v[18:33]
	s_setprio 0
	s_branch .Lpostpv_slc

; #define LAS __attribute__((address_space(3)))
; __global__ void __launch_bounds__(NTHREADS, 2) fwd_megakernel(Params P0) {
;     extern __shared__ __attribute__((aligned(16))) unsigned char shm[];
;     LAS unsigned char* lds = (LAS unsigned char*)shm;
	.amdhsa_kernel _Z14fwd_megakernel6Params
		.amdhsa_group_segment_fixed_size 256
		.amdhsa_private_segment_fixed_size 0
		.amdhsa_kernarg_size 456
		.amdhsa_user_sgpr_count 2
		.amdhsa_user_sgpr_dispatch_ptr 0
		.amdhsa_user_sgpr_queue_ptr 0
		.amdhsa_user_sgpr_kernarg_segment_ptr 1
		.amdhsa_user_sgpr_dispatch_id 0
		.amdhsa_user_sgpr_kernarg_preload_length 0
		.amdhsa_user_sgpr_kernarg_preload_offset 0
		.amdhsa_user_sgpr_private_segment_size 0
		.amdhsa_uses_dynamic_stack 0
		.amdhsa_enable_private_segment 0
		.amdhsa_system_sgpr_workgroup_id_x 1
		.amdhsa_system_sgpr_workgroup_id_y 0
		.amdhsa_system_sgpr_workgroup_id_z 0
		.amdhsa_system_sgpr_workgroup_info 0
		.amdhsa_system_vgpr_workitem_id 2
		.amdhsa_next_free_vgpr 253
		.amdhsa_next_free_sgpr 99
		.amdhsa_accum_offset 256
		.amdhsa_reserve_vcc 1
		.amdhsa_float_round_mode_32 0
		.amdhsa_float_round_mode_16_64 0
		.amdhsa_float_denorm_mode_32 3
		.amdhsa_float_denorm_mode_16_64 3
		.amdhsa_dx10_clamp 1
		.amdhsa_ieee_mode 1
		.amdhsa_fp16_overflow 0
		.amdhsa_tg_split 0
		.amdhsa_exception_fp_ieee_invalid_op 0
		.amdhsa_exception_fp_denorm_src 0
		.amdhsa_exception_fp_ieee_div_zero 0
		.amdhsa_exception_fp_ieee_overflow 0
		.amdhsa_exception_fp_ieee_underflow 0
		.amdhsa_exception_fp_ieee_inexact 0
		.amdhsa_exception_int_div_zero 0
	.end_amdhsa_kernel

amdhsa.kernels:
  - .agpr_count:     0
    .args:
      - .offset:         0
        .size:           200
        .value_kind:     by_value
      - .offset:         200
        .size:           4
        .value_kind:     hidden_block_count_x
      - .offset:         204
        .size:           4
        .value_kind:     hidden_block_count_y
      - .offset:         208
        .size:           4
        .value_kind:     hidden_block_count_z
      - .offset:         212
        .size:           2
        .value_kind:     hidden_group_size_x
      - .offset:         214
        .size:           2
        .value_kind:     hidden_group_size_y
      - .offset:         216
        .size:           2
        .value_kind:     hidden_group_size_z
      - .offset:         218
        .size:           2
        .value_kind:     hidden_remainder_x
      - .offset:         220
        .size:           2
        .value_kind:     hidden_remainder_y
      - .offset:         222
        .size:           2
        .value_kind:     hidden_remainder_z
      - .offset:         240
        .size:           8
        .value_kind:     hidden_global_offset_x
      - .offset:         248
        .size:           8
        .value_kind:     hidden_global_offset_y
      - .offset:         256
        .size:           8
        .value_kind:     hidden_global_offset_z
      - .offset:         264
        .size:           2
        .value_kind:     hidden_grid_dims
      - .offset:         288
        .size:           8
        .value_kind:     hidden_multigrid_sync_arg
      - .offset:         320
        .size:           4
        .value_kind:     hidden_dynamic_lds_size
    .group_segment_fixed_size: 256
    .kernarg_segment_align: 8
    .kernarg_segment_size: 456
    .language:       OpenCL C
    .language_version:
      - 2
      - 0
    .max_flat_workgroup_size: 512
    .name:           _Z14fwd_megakernel6Params
    .private_segment_fixed_size: 0
    .sgpr_count:     105
    .sgpr_spill_count: 2
    .symbol:         _Z14fwd_megakernel6Params.kd
    .uniform_work_group_size: 1
    .uses_dynamic_stack: false
    .vgpr_count:     253
    .vgpr_spill_count: 0
    .wavefront_size: 64
